# v14: v12 + LN1 row loop prefetches row A one trip ahead (v68-99), copies at loop top
# baseline (speedup 1.0000x reference)
; __device__ __forceinline__ int row_perm(int m) { const int j = m >> 11, r = m & 2047; return (11 - 3 * (j & 3) - (j >> 2)) * 2048 + r; }
; __device__ __forceinline__ kaptr ka_fresh() { kaptr p = (kaptr)__builtin_amdgcn_kernarg_segment_ptr(); asm volatile("" : "+s"(p)); return p; }
; #define KA_WS(ka) (*(unsigned char* const __attribute__((address_space(4)))*)((ka) + 216))
; #define PHASE_IDS() int vcu = vcu0, G = G0; asm volatile("" : "+s"(vcu), "+s"(G)); const int ngw = G * NWAVES; (void)ngw; int tid = tid0; asm volatile("" : "+v"(tid)); const int lane = tid & 63, wave = __builtin_amdgcn_readfirstlane(tid >> 6), gw = vcu * NWAVES + wave; (void)lane; (void)gw
; __device__ __forceinline__ void ln_fetch_b(const bf16* src, v4u (&raw)[8], int lane) {
;     const v4u* xr = (const v4u*)src + lane;
; #pragma unroll
;     for (int j = 0; j < 8; ++j) raw[j] = xr[64 * j];
; }
; __global__ void __launch_bounds__(NT, 2) fwd_kernel(Args args_unused) {
;     ...
;         if (IN(P + 5)) {
;             PHASE_IDS(); kaptr ka = ka_fresh(); unsigned char* ws = KA_WS(ka);
;             for (int m0 = gw; m0 < MTOK; m0 += 2 * ngw) { const int mA = row_perm(m0), mB = row_perm(m0 + ngw < MTOK ? m0 + ngw : m0); const bool hasB = m0 + ngw < MTOK;
;                 v4u rawA[8], rawB[8]; ln_fetch_b(WSP(const bf16, WS_XR) + (size_t)mA * DM, rawA, lane); ln_fetch_b(WSP(const bf16, WS_XR) + (size_t)mB * DM, rawB, lane);
.LBB0_977:
	v_readlane_b32 s4, v252, 6
	v_readlane_b32 s6, v252, 8
	v_readlane_b32 s7, v252, 9
	s_mov_b64 s[10:11], s[6:7]
	s_cmp_le_i32 s10, s3
	s_cselect_b64 s[6:7], -1, 0
	s_cmp_lt_i32 s3, s11
	s_cselect_b64 s[8:9], -1, 0
	s_and_b64 s[10:11], s[6:7], s[8:9]
	s_andn2_b64 vcc, exec, s[10:11]
	v_readlane_b32 s5, v252, 7
	s_cbranch_vccnz .LBB0_991
	v_readlane_b32 s3, v252, 5
	v_readlane_b32 s8, v252, 4
	v_mov_b32_e32 v1, v0
	s_lshl_b32 s3, s3, 3
	v_readfirstlane_b32 s6, v1
	s_ashr_i32 s6, s6, 6
	s_add_i32 s3, s6, s3
	v_readlane_b32 s6, v252, 0
	v_readlane_b32 s7, v252, 1
	s_cmpk_gt_i32 s3, 0x5fff
	s_cbranch_scc1 .LBB0_991
	s_load_dwordx2 s[14:15], s[6:7], 0xd8
	s_load_dwordx4 s[28:31], s[6:7], 0xa0
	v_and_b32_e32 v4, 63, v1
	v_lshlrev_b32_e32 v182, 4, v4
	s_mov_b64 s[4:5], 0x96a00000
	s_waitcnt lgkmcnt(0)
	v_lshl_add_u64 v[2:3], s[14:15], 0, v[182:183]
	v_and_b32_e32 v1, 64, v223
	v_lshl_add_u64 v[66:67], v[2:3], 0, s[4:5]
	v_add_u32_e32 v2, 64, v1
	v_xor_b32_e32 v1, 1, v223
	v_cmp_lt_i32_e32 vcc, v1, v2
	v_xor_b32_e32 v3, 2, v223
	v_readlane_b32 s4, v251, 10
	v_cndmask_b32_e32 v1, v223, v1, vcc
	v_cmp_lt_i32_e32 vcc, v3, v2
	v_readlane_b32 s5, v251, 11
	s_lshl_b32 s26, s8, 3
	v_cndmask_b32_e32 v3, v223, v3, vcc
	v_lshlrev_b32_e32 v152, 2, v3
	v_xor_b32_e32 v3, 4, v223
	v_cmp_lt_i32_e32 vcc, v3, v2
	s_lshl_b64 s[6:7], s[4:5], 2
	s_add_u32 s16, s28, s6
	v_cndmask_b32_e32 v3, v223, v3, vcc
	v_lshlrev_b32_e32 v153, 2, v3
	v_xor_b32_e32 v3, 8, v223
	v_cmp_lt_i32_e32 vcc, v3, v2
	s_addc_u32 s17, s29, s7
	s_add_u32 s30, s30, s6
	v_cndmask_b32_e32 v3, v223, v3, vcc
	v_lshlrev_b32_e32 v154, 2, v3
	v_xor_b32_e32 v3, 16, v223
	v_cmp_lt_i32_e32 vcc, v3, v2
	v_lshlrev_b32_e32 v182, 5, v4
	s_addc_u32 s31, s31, s7
	v_cndmask_b32_e32 v3, v223, v3, vcc
	v_lshlrev_b32_e32 v155, 2, v3
	v_xor_b32_e32 v3, 32, v223
	v_cmp_lt_i32_e32 vcc, v3, v2
	s_add_u32 s27, s14, 0xe00000
	v_lshl_add_u64 v[68:69], s[16:17], 0, v[182:183]
	v_cndmask_b32_e32 v2, v223, v3, vcc
	v_lshlrev_b32_e32 v156, 2, v2
	v_or_b32_e32 v2, 0x800, v182
	v_mov_b32_e32 v3, v183
	v_lshl_add_u64 v[72:73], s[16:17], 0, v[2:3]
	v_lshl_add_u64 v[74:75], s[30:31], 0, v[2:3]
	v_or_b32_e32 v2, 0x1000, v182
	v_lshl_add_u64 v[76:77], s[16:17], 0, v[2:3]
	v_lshl_add_u64 v[78:79], s[30:31], 0, v[2:3]
	v_or_b32_e32 v2, 0x1800, v182
	v_lshl_add_u64 v[80:81], s[16:17], 0, v[2:3]
	v_lshl_add_u64 v[82:83], s[30:31], 0, v[2:3]
	v_or_b32_e32 v2, 0x2000, v182
	v_lshl_add_u64 v[84:85], s[16:17], 0, v[2:3]
	v_lshl_add_u64 v[86:87], s[30:31], 0, v[2:3]
	v_or_b32_e32 v2, 0x2800, v182
	v_lshl_add_u64 v[70:71], s[30:31], 0, v[182:183]
	v_lshl_add_u64 v[88:89], s[16:17], 0, v[2:3]
	v_lshl_add_u64 v[90:91], s[30:31], 0, v[2:3]
	v_or_b32_e32 v2, 0x3000, v182
	v_or_b32_e32 v182, 0x3800, v182
	s_addc_u32 s28, s15, 0
	v_lshl_add_u64 v[96:97], s[16:17], 0, v[182:183]
	v_lshl_add_u64 v[98:99], s[30:31], 0, v[182:183]
	v_lshlrev_b32_e32 v182, 3, v4
	s_add_u32 s29, s14, 0xe40000
	v_lshl_add_u64 v[92:93], s[16:17], 0, v[2:3]
	v_lshl_add_u64 v[94:95], s[30:31], 0, v[2:3]
	v_lshl_add_u64 v[2:3], s[14:15], 0, v[182:183]
	s_mov_b64 s[4:5], 0x1000000
	s_addc_u32 s42, s15, 0
	v_lshlrev_b32_e32 v1, 2, v1
	v_cmp_eq_u32_e64 s[6:7], 0, v4
	s_lshl_b32 s43, s8, 4
	v_lshl_add_u64 v[100:101], v[2:3], 0, s[4:5]
	v_lshlrev_b32_e32 v162, 4, v0
	v_add_u32_e32 v163, 0x2000, v162
	global_load_dwordx4 v[164:167], v162, s[16:17]
	global_load_dwordx4 v[168:171], v163, s[16:17]
	global_load_dwordx4 v[172:175], v162, s[30:31]
	global_load_dwordx4 v[176:179], v163, s[30:31]
	v_and_b32_e32 v181, 63, v0
	v_lshlrev_b32_e32 v181, 5, v181
	v_add_u32_e32 v181, 0x12000, v181
	v_add_u32_e32 v180, 0x12000, v162
	s_waitcnt vmcnt(0)
	ds_write_b128 v180, v[164:167]
	ds_write_b128 v180, v[168:171] offset:8192
	ds_write_b128 v180, v[172:175] offset:16384
	ds_write_b128 v180, v[176:179] offset:24576
	s_waitcnt lgkmcnt(0)
	s_barrier
	s_mov_b32 s100, s3
	s_bfe_u32 s101, s100, 0x2000b
	s_mul_i32 s101, s101, 0x1ffffd
	s_ashr_i32 vcc_lo, s100, 13
	s_sub_i32 s101, s101, vcc_lo
	s_and_b32 vcc_lo, s100, 0x7ff
	s_lshl_b32 s101, s101, 11
	s_or_b32 s100, s101, vcc_lo
	s_add_i32 s100, s100, 0x5800
	s_ashr_i32 s101, s100, 31
	s_lshl_b64 s[100:101], s[100:101], 13
	v_lshl_add_u64 v[162:163], v[66:67], 0, s[100:101]
	global_load_dwordx4 v[68:71], v[162:163], off
	global_load_dwordx4 v[72:75], v[162:163], off offset:1024
	global_load_dwordx4 v[76:79], v[162:163], off offset:2048
	global_load_dwordx4 v[80:83], v[162:163], off offset:3072
	s_add_u32 s100, s100, s25
	s_addc_u32 s101, s101, 0
	v_lshl_add_u64 v[162:163], v[66:67], 0, s[100:101]
	global_load_dwordx4 v[84:87], v[162:163], off
	global_load_dwordx4 v[88:91], v[162:163], off offset:1024
	global_load_dwordx4 v[92:95], v[162:163], off offset:2048
	global_load_dwordx4 v[96:99], v[162:163], off offset:3072
	s_branch .LBB0_982

; __device__ __forceinline__ f32x4 h4lo(const u32x4 w) { return (f32x4){hlo(w.x), hhi(w.x), hlo(w.y), hhi(w.y)}; }
; __device__ __forceinline__ f32x4 h4hi(const u32x4 w) { return (f32x4){hlo(w.z), hhi(w.z), hlo(w.w), hhi(w.w)}; }
; __device__ __forceinline__ int row_perm(int m) { const int j = m >> 11, r = m & 2047; return (11 - 3 * (j & 3) - (j >> 2)) * 2048 + r; }
; __device__ __forceinline__ void ln_fetch_b(const bf16* src, v4u (&raw)[8], int lane) {
;     const v4u* xr = (const v4u*)src + lane;
; #pragma unroll
;     for (int j = 0; j < 8; ++j) raw[j] = xr[64 * j];
; }
; __device__ __forceinline__ void ln_load_b(const v4u (&raw)[8], f32x4 (&v)[16], float& mean, float& rstd, int lane) {
;     float s = 0.f;
; #pragma unroll
;     for (int j = 0; j < 8; ++j) { const v4u w = raw[j]; v[2 * j] = pg8::h4lo(w); v[2 * j + 1] = pg8::h4hi(w);
;         s += ((v[2 * j].x + v[2 * j].y) + (v[2 * j].z + v[2 * j].w)) + ((v[2 * j + 1].x + v[2 * j + 1].y) + (v[2 * j + 1].z + v[2 * j + 1].w)); }
;     mean = wave_sum(s) * (1.f / 4096.f); float s2 = 0.f;
; __global__ void __launch_bounds__(NT, 2) fwd_kernel(Args args_unused) {
;     ...
;             for (int m0 = gw; m0 < MTOK; m0 += 2 * ngw) { const int mA = row_perm(m0), mB = row_perm(m0 + ngw < MTOK ? m0 + ngw : m0); const bool hasB = m0 + ngw < MTOK;
;                 v4u rawA[8], rawB[8]; ln_fetch_b(WSP(const bf16, WS_XR) + (size_t)mA * DM, rawA, lane); ln_fetch_b(WSP(const bf16, WS_XR) + (size_t)mB * DM, rawB, lane);
.LBB0_982:
	s_bfe_u32 s9, s3, 0x2000b
	s_mul_i32 s9, s9, 0x1ffffd
	s_ashr_i32 s14, s3, 13
	s_sub_i32 s9, s9, s14
	s_and_b32 s8, s3, 0x7ff
	s_lshl_b32 s9, s9, 11
	s_or_b32 s8, s9, s8
	s_add_i32 s36, s8, 0x5800
	s_add_i32 s14, s26, s3
	s_cmpk_lt_i32 s14, 0x6000
	s_cselect_b64 s[16:17], -1, 0
	s_and_b64 s[8:9], s[16:17], exec
	s_cselect_b32 s8, s14, s3
	s_ashr_i32 s37, s36, 31
	s_lshl_b64 s[14:15], s[36:37], 13
	v_lshl_add_u64 v[2:3], v[66:67], 0, s[14:15]
	v_add_co_u32_e32 v2, vcc, s25, v2
	v_mov_b32_e32 v4, v183
	s_nop 0
	v_addc_co_u32_e32 v3, vcc, 0, v3, vcc
	s_bfe_u32 s14, s8, 0x2000b
	s_and_b32 s9, s8, 0x7ff
	s_mul_i32 s14, s14, 0x1ffffd
	s_ashr_i32 s8, s8, 13
	s_sub_i32 s8, s14, s8
	s_lshl_b32 s8, s8, 11
	s_or_b32 s8, s8, s9
	s_add_i32 s14, s8, 0x5800
	s_ashr_i32 s15, s14, 31
	s_lshl_b64 s[8:9], s[14:15], 13
	s_waitcnt vmcnt(0)
	v_mov_b64_e32 v[62:63], v[68:69]
	v_mov_b64_e32 v[64:65], v[70:71]
	v_mov_b64_e32 v[58:59], v[72:73]
	v_mov_b64_e32 v[60:61], v[74:75]
	v_mov_b64_e32 v[54:55], v[76:77]
	v_mov_b64_e32 v[56:57], v[78:79]
	v_mov_b64_e32 v[50:51], v[80:81]
	v_mov_b64_e32 v[52:53], v[82:83]
	v_mov_b64_e32 v[42:43], v[84:85]
	v_mov_b64_e32 v[44:45], v[86:87]
	v_mov_b64_e32 v[38:39], v[88:89]
	v_mov_b64_e32 v[40:41], v[90:91]
	v_mov_b64_e32 v[34:35], v[92:93]
	v_mov_b64_e32 v[36:37], v[94:95]
	v_mov_b64_e32 v[46:47], v[96:97]
	v_mov_b64_e32 v[48:49], v[98:99]
	s_add_i32 s100, s3, s43
	s_cmpk_lt_i32 s100, 0x6000
	s_cselect_b32 s100, s100, s3
	s_bfe_u32 s101, s100, 0x2000b
	s_mul_i32 s101, s101, 0x1ffffd
	s_ashr_i32 vcc_lo, s100, 13
	s_sub_i32 s101, s101, vcc_lo
	s_and_b32 vcc_lo, s100, 0x7ff
	s_lshl_b32 s101, s101, 11
	s_or_b32 s100, s101, vcc_lo
	s_add_i32 s100, s100, 0x5800
	s_ashr_i32 s101, s100, 31
	s_lshl_b64 s[100:101], s[100:101], 13
	v_lshl_add_u64 v[162:163], v[66:67], 0, s[100:101]
	global_load_dwordx4 v[68:71], v[162:163], off
	global_load_dwordx4 v[72:75], v[162:163], off offset:1024
	global_load_dwordx4 v[76:79], v[162:163], off offset:2048
	global_load_dwordx4 v[80:83], v[162:163], off offset:3072
	s_add_u32 s100, s100, s25
	s_addc_u32 s101, s101, 0
	v_lshl_add_u64 v[162:163], v[66:67], 0, s[100:101]
	global_load_dwordx4 v[84:87], v[162:163], off
	global_load_dwordx4 v[88:91], v[162:163], off offset:1024
	global_load_dwordx4 v[92:95], v[162:163], off offset:2048
	global_load_dwordx4 v[96:99], v[162:163], off offset:3072
	v_cvt_f32_f16_e32 v2, v62
	v_cvt_f32_f16_sdwa v6, v62 dst_sel:DWORD dst_unused:UNUSED_PAD src0_sel:WORD_1
	v_cvt_f32_f16_e32 v8, v63
	v_cvt_f32_f16_sdwa v10, v63 dst_sel:DWORD dst_unused:UNUSED_PAD src0_sel:WORD_1
	v_cvt_f32_f16_e32 v3, v64
	v_cvt_f32_f16_sdwa v7, v64 dst_sel:DWORD dst_unused:UNUSED_PAD src0_sel:WORD_1
	v_cvt_f32_f16_e32 v9, v65
	v_cvt_f32_f16_sdwa v11, v65 dst_sel:DWORD dst_unused:UNUSED_PAD src0_sel:WORD_1
	v_cvt_f32_f16_e32 v12, v58
	v_cvt_f32_f16_sdwa v14, v58 dst_sel:DWORD dst_unused:UNUSED_PAD src0_sel:WORD_1
	v_cvt_f32_f16_e32 v13, v59
	v_cvt_f32_f16_sdwa v15, v59 dst_sel:DWORD dst_unused:UNUSED_PAD src0_sel:WORD_1
	v_cvt_f32_f16_e32 v16, v60
	v_cvt_f32_f16_sdwa v18, v60 dst_sel:DWORD dst_unused:UNUSED_PAD src0_sel:WORD_1
	v_cvt_f32_f16_e32 v17, v61
	v_cvt_f32_f16_sdwa v19, v61 dst_sel:DWORD dst_unused:UNUSED_PAD src0_sel:WORD_1
	v_pk_add_f32 v[2:3], v[2:3], v[6:7]
	v_pk_add_f32 v[6:7], v[8:9], v[10:11]
	v_pk_add_f32 v[8:9], v[12:13], v[14:15]
	v_pk_add_f32 v[10:11], v[16:17], v[18:19]
	v_pk_add_f32 v[2:3], v[2:3], v[6:7]
	v_cvt_f32_f16_e32 v20, v54
	v_cvt_f32_f16_sdwa v22, v54 dst_sel:DWORD dst_unused:UNUSED_PAD src0_sel:WORD_1
	v_cvt_f32_f16_e32 v24, v55
	v_cvt_f32_f16_sdwa v26, v55 dst_sel:DWORD dst_unused:UNUSED_PAD src0_sel:WORD_1
	v_cvt_f32_f16_e32 v112, v56
	v_cvt_f32_f16_sdwa v113, v56 dst_sel:DWORD dst_unused:UNUSED_PAD src0_sel:WORD_1
	v_cvt_f32_f16_e32 v114, v57
	v_cvt_f32_f16_sdwa v115, v57 dst_sel:DWORD dst_unused:UNUSED_PAD src0_sel:WORD_1
	v_pk_add_f32 v[6:7], v[8:9], v[8:9] op_sel:[0,1] op_sel_hi:[1,0]
	v_pk_add_f32 v[8:9], v[10:11], v[10:11] op_sel:[0,1] op_sel_hi:[1,0]
	v_pk_add_f32 v[2:3], v[2:3], v[2:3] op_sel:[0,1] op_sel_hi:[1,0]
	v_cvt_f32_f16_sdwa v5, v50 dst_sel:DWORD dst_unused:UNUSED_PAD src0_sel:WORD_1
	v_cvt_f32_f16_e32 v21, v52
	v_cvt_f32_f16_sdwa v23, v52 dst_sel:DWORD dst_unused:UNUSED_PAD src0_sel:WORD_1
	v_cvt_f32_f16_e32 v25, v53
	v_cvt_f32_f16_sdwa v27, v53 dst_sel:DWORD dst_unused:UNUSED_PAD src0_sel:WORD_1
	v_cvt_f32_f16_e32 v7, v51
	v_cvt_f32_f16_sdwa v9, v51 dst_sel:DWORD dst_unused:UNUSED_PAD src0_sel:WORD_1
	v_cvt_f32_f16_e32 v3, v50
	v_add_f32_e32 v20, v22, v20
	v_add_f32_e32 v22, v26, v24
	v_add_f32_e32 v24, v113, v112
	v_add_f32_e32 v26, v115, v114
	v_pk_add_f32 v[10:11], v[20:21], v[22:23]
	v_pk_add_f32 v[12:13], v[24:25], v[26:27]
	v_pk_add_f32 v[6:7], v[6:7], v[8:9]
	v_pk_add_f32 v[2:3], v[2:3], v[4:5]
	v_cvt_f32_f16_e32 v28, v42
	v_cvt_f32_f16_sdwa v30, v42 dst_sel:DWORD dst_unused:UNUSED_PAD src0_sel:WORD_1
	v_cvt_f32_f16_e32 v32, v43
	v_cvt_f32_f16_sdwa v102, v43 dst_sel:DWORD dst_unused:UNUSED_PAD src0_sel:WORD_1
	v_cvt_f32_f16_e32 v29, v44
	v_cvt_f32_f16_sdwa v31, v44 dst_sel:DWORD dst_unused:UNUSED_PAD src0_sel:WORD_1
	v_cvt_f32_f16_e32 v33, v45
	v_cvt_f32_f16_sdwa v103, v45 dst_sel:DWORD dst_unused:UNUSED_PAD src0_sel:WORD_1
	v_pk_add_f32 v[10:11], v[10:11], v[12:13]
	v_pk_add_f32 v[2:3], v[2:3], v[6:7]
	v_cvt_f32_f16_e32 v104, v38
	v_cvt_f32_f16_sdwa v106, v38 dst_sel:DWORD dst_unused:UNUSED_PAD src0_sel:WORD_1
	v_cvt_f32_f16_e32 v105, v39
	v_cvt_f32_f16_sdwa v107, v39 dst_sel:DWORD dst_unused:UNUSED_PAD src0_sel:WORD_1
	v_cvt_f32_f16_e32 v108, v40
	v_cvt_f32_f16_sdwa v110, v40 dst_sel:DWORD dst_unused:UNUSED_PAD src0_sel:WORD_1
; __device__ __forceinline__ f32x4 h4lo(const u32x4 w) { return (f32x4){hlo(w.x), hhi(w.x), hlo(w.y), hhi(w.y)}; }
; __device__ __forceinline__ f32x4 h4hi(const u32x4 w) { return (f32x4){hlo(w.z), hhi(w.z), hlo(w.w), hhi(w.w)}; }
; __device__ __forceinline__ void ln_load_b(const v4u (&raw)[8], f32x4 (&v)[16], float& mean, float& rstd, int lane) {
;     float s = 0.f;
; #pragma unroll
;     for (int j = 0; j < 8; ++j) { const v4u w = raw[j]; v[2 * j] = pg8::h4lo(w); v[2 * j + 1] = pg8::h4hi(w);
;         s += ((v[2 * j].x + v[2 * j].y) + (v[2 * j].z + v[2 * j].w)) + ((v[2 * j + 1].x + v[2 * j + 1].y) + (v[2 * j + 1].z + v[2 * j + 1].w)); }
;     mean = wave_sum(s) * (1.f / 4096.f); float s2 = 0.f;
; #pragma unroll
;     for (int j = 0; j < 16; ++j) { v[j] = v[j] - mean; s2 += (v[j].x * v[j].x + v[j].y * v[j].y) + (v[j].z * v[j].z + v[j].w * v[j].w); }
;     rstd = 1.f / sqrtf(wave_sum(s2) * (1.f / 4096.f) + 1e-5f);
	v_cvt_f32_f16_e32 v109, v41
	v_cvt_f32_f16_sdwa v111, v41 dst_sel:DWORD dst_unused:UNUSED_PAD src0_sel:WORD_1
	v_pk_add_f32 v[2:3], v[2:3], v[10:11]
	v_cvt_f32_f16_sdwa v5, v35 dst_sel:DWORD dst_unused:UNUSED_PAD src0_sel:WORD_1
	v_pk_add_f32 v[2:3], v[2:3], v[2:3] op_sel:[0,1] op_sel_hi:[1,0]
	v_cvt_f32_f16_e32 v7, v36
	v_cvt_f32_f16_e32 v3, v35
	v_cvt_f32_f16_sdwa v8, v36 dst_sel:DWORD dst_unused:UNUSED_PAD src0_sel:WORD_1
	v_cvt_f32_f16_e32 v9, v37
	v_cvt_f32_f16_sdwa v10, v37 dst_sel:DWORD dst_unused:UNUSED_PAD src0_sel:WORD_1
	v_pk_add_f32 v[14:15], v[28:29], v[30:31]
	v_pk_add_f32 v[16:17], v[32:33], v[102:103]
	v_pk_add_f32 v[18:19], v[104:105], v[106:107]
	v_pk_add_f32 v[20:21], v[108:109], v[110:111]
	v_pk_add_f32 v[12:13], v[14:15], v[16:17]
	v_cvt_f32_f16_e32 v116, v34
	v_cvt_f32_f16_sdwa v117, v34 dst_sel:DWORD dst_unused:UNUSED_PAD src0_sel:WORD_1
	v_pk_add_f32 v[14:15], v[18:19], v[18:19] op_sel:[0,1] op_sel_hi:[1,0]
	v_pk_add_f32 v[16:17], v[20:21], v[20:21] op_sel:[0,1] op_sel_hi:[1,0]
	v_pk_add_f32 v[12:13], v[12:13], v[12:13] op_sel:[0,1] op_sel_hi:[1,0]
	v_add_f32_e32 v6, v5, v3
	v_add_f32_e32 v8, v8, v7
	v_add_f32_e32 v10, v10, v9
	v_cvt_f32_f16_e32 v3, v46
	v_cvt_f32_f16_sdwa v13, v46 dst_sel:DWORD dst_unused:UNUSED_PAD src0_sel:WORD_1
	v_cvt_f32_f16_e32 v15, v47
	v_cvt_f32_f16_sdwa v17, v47 dst_sel:DWORD dst_unused:UNUSED_PAD src0_sel:WORD_1
	v_cvt_f32_f16_e32 v5, v48
	v_cvt_f32_f16_sdwa v7, v48 dst_sel:DWORD dst_unused:UNUSED_PAD src0_sel:WORD_1
	v_cvt_f32_f16_e32 v9, v49
	v_cvt_f32_f16_sdwa v11, v49 dst_sel:DWORD dst_unused:UNUSED_PAD src0_sel:WORD_1
	v_add_f32_e32 v4, v117, v116
	v_pk_add_f32 v[2:3], v[2:3], v[12:13]
	v_pk_add_f32 v[12:13], v[14:15], v[16:17]
	v_pk_add_f32 v[4:5], v[4:5], v[6:7]
	v_pk_add_f32 v[6:7], v[8:9], v[10:11]
	v_pk_add_f32 v[2:3], v[2:3], v[12:13]
	v_pk_add_f32 v[4:5], v[4:5], v[6:7]
	s_nop 0
	v_pk_add_f32 v[2:3], v[2:3], v[4:5]
	s_nop 0
	v_add_f32_e32 v2, v2, v3
	s_nop 1
	v_mov_b32_dpp v3, v2 quad_perm:[1,0,3,2] row_mask:0xf bank_mask:0xf
	s_waitcnt lgkmcnt(0)
	v_add_f32_e32 v2, v2, v3
	s_nop 1
	v_mov_b32_dpp v3, v2 quad_perm:[2,3,0,1] row_mask:0xf bank_mask:0xf
	s_waitcnt lgkmcnt(0)
	v_add_f32_e32 v4, v2, v3
	s_nop 1
	v_mov_b32_dpp v5, v4 row_half_mirror row_mask:0xf bank_mask:0xf
	v_lshl_add_u64 v[2:3], v[66:67], 0, s[8:9]
	global_load_dwordx4 v[30:33], v[2:3], off
	global_load_dwordx4 v[26:29], v[2:3], off offset:1024
	global_load_dwordx4 v[22:25], v[2:3], off offset:2048
	global_load_dwordx4 v[18:21], v[2:3], off offset:3072
	v_add_co_u32_e32 v2, vcc, s25, v2
	s_waitcnt lgkmcnt(0)
	v_add_f32_e32 v4, v4, v5
	s_nop 1
	v_mov_b32_dpp v5, v4 row_mirror row_mask:0xf bank_mask:0xf
	v_addc_co_u32_e32 v3, vcc, 0, v3, vcc
	s_waitcnt lgkmcnt(0)
	v_add_f32_e32 v4, v4, v5
	v_mov_b32_e32 v5, v4
	s_nop 1
	v_permlane16_swap_b32_e32 v5, v4
	s_waitcnt lgkmcnt(0)
	v_add_f32_e32 v102, v4, v5
	v_mov_b32_e32 v103, v102
	s_nop 1
	v_permlane32_swap_b32_e32 v103, v102
	global_load_dwordx4 v[14:17], v[2:3], off
	global_load_dwordx4 v[10:13], v[2:3], off offset:1024
	global_load_dwordx4 v[6:9], v[2:3], off offset:2048
	s_nop 0
	global_load_dwordx4 v[2:5], v[2:3], off offset:3072
	s_waitcnt lgkmcnt(0)
	v_add_f32_e32 v146, v102, v103
	v_fma_mix_f32 v103, v146, s87, v63 op_sel:[0,0,1] op_sel_hi:[0,0,1]
	v_fma_mix_f32 v109, v146, s87, v62 op_sel:[0,0,1] op_sel_hi:[0,0,1]
	v_fma_mix_f32 v102, v146, s87, v63 op_sel_hi:[0,0,1]
	v_fma_mix_f32 v108, v146, s87, v62 op_sel_hi:[0,0,1]
	v_mul_f32_e32 v62, v109, v109
	v_mul_f32_e32 v63, v103, v103
	v_fmac_f32_e32 v62, v108, v108
	v_fmac_f32_e32 v63, v102, v102
	v_fma_mix_f32 v111, v146, s87, v65 op_sel:[0,0,1] op_sel_hi:[0,0,1]
	v_fma_mix_f32 v145, v146, s87, v64 op_sel:[0,0,1] op_sel_hi:[0,0,1]
	v_fma_mix_f32 v105, v146, s87, v59 op_sel:[0,0,1] op_sel_hi:[0,0,1]
	v_fma_mix_f32 v107, v146, s87, v58 op_sel:[0,0,1] op_sel_hi:[0,0,1]
	v_add_f32_e32 v62, v62, v63
	v_fma_mix_f32 v110, v146, s87, v65 op_sel_hi:[0,0,1]
	v_fma_mix_f32 v144, v146, s87, v64 op_sel_hi:[0,0,1]
	v_mul_f32_e32 v63, v145, v145
	v_mul_f32_e32 v64, v111, v111
	v_fma_mix_f32 v104, v146, s87, v59 op_sel_hi:[0,0,1]
	v_fma_mix_f32 v106, v146, s87, v58 op_sel_hi:[0,0,1]
	v_mul_f32_e32 v58, v107, v107
	v_mul_f32_e32 v59, v105, v105
	v_fmac_f32_e32 v63, v144, v144
	v_fmac_f32_e32 v64, v110, v110
	v_fmac_f32_e32 v58, v106, v106
	v_fmac_f32_e32 v59, v104, v104
	v_fma_mix_f32 v117, v146, s87, v61 op_sel:[0,0,1] op_sel_hi:[0,0,1]
	v_fma_mix_f32 v119, v146, s87, v60 op_sel:[0,0,1] op_sel_hi:[0,0,1]
	v_fma_mix_f32 v113, v146, s87, v55 op_sel:[0,0,1] op_sel_hi:[0,0,1]
	v_fma_mix_f32 v115, v146, s87, v54 op_sel:[0,0,1] op_sel_hi:[0,0,1]
	v_add_f32_e32 v63, v63, v64
	v_add_f32_e32 v58, v58, v59
	v_fma_mix_f32 v116, v146, s87, v61 op_sel_hi:[0,0,1]
	v_fma_mix_f32 v118, v146, s87, v60 op_sel_hi:[0,0,1]
	v_mul_f32_e32 v59, v119, v119
	v_mul_f32_e32 v60, v117, v117
	v_fma_mix_f32 v112, v146, s87, v55 op_sel_hi:[0,0,1]
	v_fma_mix_f32 v114, v146, s87, v54 op_sel_hi:[0,0,1]
	v_mul_f32_e32 v54, v115, v115
	v_mul_f32_e32 v55, v113, v113
	v_add_f32_e32 v62, v62, v63
	v_fmac_f32_e32 v59, v118, v118
	v_fmac_f32_e32 v60, v116, v116
	v_fmac_f32_e32 v54, v114, v114
	v_fmac_f32_e32 v55, v112, v112
	v_fma_mix_f32 v125, v146, s87, v57 op_sel:[0,0,1] op_sel_hi:[0,0,1]
	v_fma_mix_f32 v127, v146, s87, v56 op_sel:[0,0,1] op_sel_hi:[0,0,1]
	v_fma_mix_f32 v121, v146, s87, v51 op_sel:[0,0,1] op_sel_hi:[0,0,1]
	v_fma_mix_f32 v123, v146, s87, v50 op_sel:[0,0,1] op_sel_hi:[0,0,1]
	v_add_f32_e32 v58, v58, v62
	v_add_f32_e32 v59, v59, v60
	v_add_f32_e32 v54, v54, v55
	v_fma_mix_f32 v124, v146, s87, v57 op_sel_hi:[0,0,1]
	v_fma_mix_f32 v126, v146, s87, v56 op_sel_hi:[0,0,1]
; __device__ __forceinline__ void ln_load_b(const v4u (&raw)[8], f32x4 (&v)[16], float& mean, float& rstd, int lane) {
;     ...
;     mean = wave_sum(s) * (1.f / 4096.f); float s2 = 0.f;
; #pragma unroll
;     for (int j = 0; j < 16; ++j) { v[j] = v[j] - mean; s2 += (v[j].x * v[j].x + v[j].y * v[j].y) + (v[j].z * v[j].z + v[j].w * v[j].w); }
;     rstd = 1.f / sqrtf(wave_sum(s2) * (1.f / 4096.f) + 1e-5f);
; }
; __device__ __forceinline__ void ln_row_qb(const v4u (&src)[8], const float* g, const float* b, signed char* dstq, float* rowinv, float* stat, int lane) {
;     f32x4 v[16]; float mean, rstd; ln_load_b(src, v, mean, rstd, lane);
;     if (lane == 0) { stat[0] = mean; stat[1] = rstd; }
	v_mul_f32_e32 v55, v127, v127
	v_mul_f32_e32 v56, v125, v125
	v_fma_mix_f32 v120, v146, s87, v51 op_sel_hi:[0,0,1]
	v_fma_mix_f32 v122, v146, s87, v50 op_sel_hi:[0,0,1]
	v_mul_f32_e32 v50, v123, v123
	v_mul_f32_e32 v51, v121, v121
	v_add_f32_e32 v58, v59, v58
	v_fmac_f32_e32 v55, v126, v126
	v_fmac_f32_e32 v56, v124, v124
	v_fmac_f32_e32 v50, v122, v122
	v_fmac_f32_e32 v51, v120, v120
	v_fma_mix_f32 v133, v146, s87, v53 op_sel:[0,0,1] op_sel_hi:[0,0,1]
	v_fma_mix_f32 v135, v146, s87, v52 op_sel:[0,0,1] op_sel_hi:[0,0,1]
	v_fma_mix_f32 v129, v146, s87, v43 op_sel:[0,0,1] op_sel_hi:[0,0,1]
	v_fma_mix_f32 v131, v146, s87, v42 op_sel:[0,0,1] op_sel_hi:[0,0,1]
	v_add_f32_e32 v54, v54, v58
	v_add_f32_e32 v55, v55, v56
	v_add_f32_e32 v50, v50, v51
	v_fma_mix_f32 v132, v146, s87, v53 op_sel_hi:[0,0,1]
	v_fma_mix_f32 v134, v146, s87, v52 op_sel_hi:[0,0,1]
	v_mul_f32_e32 v51, v135, v135
	v_mul_f32_e32 v52, v133, v133
	v_fma_mix_f32 v128, v146, s87, v43 op_sel_hi:[0,0,1]
	v_fma_mix_f32 v130, v146, s87, v42 op_sel_hi:[0,0,1]
	v_mul_f32_e32 v42, v131, v131
	v_mul_f32_e32 v43, v129, v129
	v_add_f32_e32 v54, v55, v54
	v_fmac_f32_e32 v51, v134, v134
	v_fmac_f32_e32 v52, v132, v132
	v_fmac_f32_e32 v42, v130, v130
	v_fmac_f32_e32 v43, v128, v128
	v_fma_mix_f32 v141, v146, s87, v45 op_sel:[0,0,1] op_sel_hi:[0,0,1]
	v_fma_mix_f32 v143, v146, s87, v44 op_sel:[0,0,1] op_sel_hi:[0,0,1]
	v_add_f32_e32 v50, v50, v54
	v_add_f32_e32 v51, v51, v52
	v_add_f32_e32 v42, v42, v43
	v_fma_mix_f32 v140, v146, s87, v45 op_sel_hi:[0,0,1]
	v_fma_mix_f32 v142, v146, s87, v44 op_sel_hi:[0,0,1]
	v_mul_f32_e32 v43, v143, v143
	v_mul_f32_e32 v44, v141, v141
	v_add_f32_e32 v50, v51, v50
	v_fmac_f32_e32 v43, v142, v142
	v_fmac_f32_e32 v44, v140, v140
	v_add_f32_e32 v42, v42, v50
	v_add_f32_e32 v43, v43, v44
	v_add_f32_e32 v50, v43, v42
	v_fma_mix_f32 v43, v146, s87, v39 op_sel:[0,0,1] op_sel_hi:[0,0,1]
	v_fma_mix_f32 v45, v146, s87, v38 op_sel:[0,0,1] op_sel_hi:[0,0,1]
	v_fma_mix_f32 v42, v146, s87, v39 op_sel_hi:[0,0,1]
	v_fma_mix_f32 v44, v146, s87, v38 op_sel_hi:[0,0,1]
	v_mul_f32_e32 v38, v45, v45
	v_mul_f32_e32 v39, v43, v43
	v_fmac_f32_e32 v38, v44, v44
	v_fmac_f32_e32 v39, v42, v42
	v_fma_mix_f32 v137, v146, s87, v41 op_sel:[0,0,1] op_sel_hi:[0,0,1]
	v_fma_mix_f32 v139, v146, s87, v40 op_sel:[0,0,1] op_sel_hi:[0,0,1]
	v_add_f32_e32 v38, v38, v39
	v_fma_mix_f32 v136, v146, s87, v41 op_sel_hi:[0,0,1]
	v_fma_mix_f32 v138, v146, s87, v40 op_sel_hi:[0,0,1]
	v_mul_f32_e32 v39, v139, v139
	v_mul_f32_e32 v40, v137, v137
	v_fmac_f32_e32 v39, v138, v138
	v_fmac_f32_e32 v40, v136, v136
	v_add_f32_e32 v38, v38, v50
	v_add_f32_e32 v39, v39, v40
	v_add_f32_e32 v40, v39, v38
	v_fma_mix_f32 v39, v146, s87, v35 op_sel:[0,0,1] op_sel_hi:[0,0,1]
	v_fma_mix_f32 v38, v146, s87, v35 op_sel_hi:[0,0,1]
	v_fma_mix_f32 v35, v146, s87, v34 op_sel:[0,0,1] op_sel_hi:[0,0,1]
	v_fma_mix_f32 v34, v146, s87, v34 op_sel_hi:[0,0,1]
	v_mul_f32_e32 v41, v35, v35
	v_mul_f32_e32 v50, v39, v39
	v_fmac_f32_e32 v41, v34, v34
	v_fmac_f32_e32 v50, v38, v38
	v_add_f32_e32 v41, v41, v50
	v_add_f32_e32 v50, v41, v40
	v_fma_mix_f32 v41, v146, s87, v37 op_sel:[0,0,1] op_sel_hi:[0,0,1]
	v_fma_mix_f32 v40, v146, s87, v37 op_sel_hi:[0,0,1]
	v_fma_mix_f32 v37, v146, s87, v36 op_sel:[0,0,1] op_sel_hi:[0,0,1]
	v_fma_mix_f32 v36, v146, s87, v36 op_sel_hi:[0,0,1]
	v_mul_f32_e32 v51, v37, v37
	v_mul_f32_e32 v52, v41, v41
	v_fmac_f32_e32 v51, v36, v36
	v_fmac_f32_e32 v52, v40, v40
	v_fma_mix_f32 v53, v146, s87, v47 op_sel:[0,0,1] op_sel_hi:[0,0,1]
	v_fma_mix_f32 v57, v146, s87, v46 op_sel:[0,0,1] op_sel_hi:[0,0,1]
	v_add_f32_e32 v51, v51, v52
	v_fma_mix_f32 v52, v146, s87, v47 op_sel_hi:[0,0,1]
	v_fma_mix_f32 v56, v146, s87, v46 op_sel_hi:[0,0,1]
	v_mul_f32_e32 v46, v57, v57
	v_mul_f32_e32 v47, v53, v53
	v_fmac_f32_e32 v46, v56, v56
	v_fmac_f32_e32 v47, v52, v52
	v_add_f32_e32 v50, v51, v50
	v_add_f32_e32 v46, v46, v47
	v_fma_mix_f32 v51, v146, s87, v49 op_sel:[0,0,1] op_sel_hi:[0,0,1]
	v_fma_mix_f32 v55, v146, s87, v48 op_sel:[0,0,1] op_sel_hi:[0,0,1]
	v_add_f32_e32 v46, v46, v50
	v_fma_mix_f32 v50, v146, s87, v49 op_sel_hi:[0,0,1]
	v_fma_mix_f32 v54, v146, s87, v48 op_sel_hi:[0,0,1]
	v_mul_f32_e32 v47, v55, v55
	v_mul_f32_e32 v48, v51, v51
	v_fmac_f32_e32 v47, v54, v54
	v_fmac_f32_e32 v48, v50, v50
	v_add_f32_e32 v47, v47, v48
	v_add_f32_e32 v46, v47, v46
	s_nop 1
	v_mov_b32_dpp v47, v46 quad_perm:[1,0,3,2] row_mask:0xf bank_mask:0xf
	s_waitcnt lgkmcnt(0)
	v_add_f32_e32 v46, v46, v47
	s_nop 1
	v_mov_b32_dpp v47, v46 quad_perm:[2,3,0,1] row_mask:0xf bank_mask:0xf
	s_waitcnt lgkmcnt(0)
	v_add_f32_e32 v46, v46, v47
	s_nop 1
	v_mov_b32_dpp v47, v46 row_half_mirror row_mask:0xf bank_mask:0xf
	s_waitcnt lgkmcnt(0)
	v_add_f32_e32 v46, v46, v47
	s_nop 1
	v_mov_b32_dpp v47, v46 row_mirror row_mask:0xf bank_mask:0xf
	s_waitcnt lgkmcnt(0)
	v_add_f32_e32 v46, v46, v47
	v_mov_b32_e32 v47, v46
	s_nop 1
	v_permlane16_swap_b32_e32 v47, v46
	s_waitcnt lgkmcnt(0)
	v_add_f32_e32 v46, v46, v47
	v_mov_b32_e32 v47, v46
	s_nop 1
	v_permlane32_swap_b32_e32 v47, v46
	s_waitcnt lgkmcnt(0)
	v_add_f32_e32 v46, v46, v47
	v_fmamk_f32 v46, v46, 0x39800000, v216
	v_mul_f32_e32 v47, 0x4f800000, v46
	v_cmp_gt_f32_e32 vcc, s95, v46
	s_nop 1
	v_cndmask_b32_e32 v46, v46, v47, vcc
	v_sqrt_f32_e32 v47, v46
	s_nop 0
	v_add_u32_e32 v48, -1, v47
	v_fma_f32 v49, -v48, v47, v46
	v_cmp_ge_f32_e64 s[8:9], 0, v49
	v_add_u32_e32 v49, 1, v47
	s_nop 0
	v_cndmask_b32_e64 v48, v47, v48, s[8:9]
	v_fma_f32 v47, -v49, v47, v46
	v_cmp_lt_f32_e64 s[8:9], 0, v47
	s_nop 1
	v_cndmask_b32_e64 v47, v48, v49, s[8:9]
	v_mul_f32_e32 v48, 0x37800000, v47
	v_cndmask_b32_e32 v47, v47, v48, vcc
	v_cmp_class_f32_e32 vcc, v46, v215
	s_nop 1
	v_cndmask_b32_e32 v46, v47, v46, vcc
	v_div_scale_f32 v47, s[8:9], v46, v46, 1.0
	v_rcp_f32_e32 v48, v47
	s_nop 0
	v_fma_f32 v49, -v47, v48, 1.0
	v_fmac_f32_e32 v48, v49, v48
	v_div_scale_f32 v49, vcc, 1.0, v46, 1.0
	v_mul_f32_e32 v58, v49, v48
	v_fma_f32 v59, -v47, v58, v49
	v_fmac_f32_e32 v58, v59, v48
	v_fma_f32 v47, -v47, v58, v49
	v_div_fmas_f32 v47, v47, v48, v58
	v_div_fixup_f32 v62, v47, v46, 1.0
	s_and_saveexec_b64 s[8:9], s[6:7]
	s_cbranch_execz .LBB0_984
	s_lshl_b32 s30, s36, 1
	s_ashr_i32 s31, s30, 31
	s_lshl_b64 s[30:31], s[30:31], 2
	s_add_u32 s30, s29, s30
	v_mul_f32_e32 v46, 0x39800000, v146
	s_addc_u32 s31, s42, s31
	v_mov_b32_e32 v47, v62
	global_store_dwordx2 v183, v[46:47], s[30:31]
